# wave-wide sums in conv LayerNorm, final norm and prologue row norms use DPP quad_perm/row_mirror + permlane swaps instead of 6-step ds_bpermute chains
# speedup vs baseline: 1.0141x; 1.0053x over previous
.LBB7_223:
	s_waitcnt vmcnt(3)
	v_mul_f32_e32 v44, v29, v29
	v_mul_f32_e32 v45, v31, v31
	v_fmac_f32_e32 v44, v28, v28
	v_fmac_f32_e32 v45, v30, v30
	v_add_f32_e32 v44, v44, v45
	s_waitcnt vmcnt(2)
	v_mul_f32_e32 v45, v25, v25
	v_mul_f32_e32 v46, v27, v27
	v_fmac_f32_e32 v45, v24, v24
	v_fmac_f32_e32 v46, v26, v26
	v_add_f32_e32 v45, v45, v46
	v_add_f32_e32 v44, v44, v45
	s_waitcnt vmcnt(1)
	v_mul_f32_e32 v45, v21, v21
	v_mul_f32_e32 v46, v23, v23
	v_fmac_f32_e32 v45, v20, v20
	v_fmac_f32_e32 v46, v22, v22
	v_add_f32_e32 v45, v45, v46
	v_add_f32_e32 v44, v44, v45
	s_waitcnt vmcnt(0)
	v_mul_f32_e32 v45, v17, v17
	v_mul_f32_e32 v46, v19, v19
	v_fmac_f32_e32 v45, v16, v16
	v_fmac_f32_e32 v46, v18, v18
	v_add_f32_e32 v45, v45, v46
	v_cmp_lt_i32_e32 vcc, v39, v38
	v_add_f32_e32 v44, v44, v45
	s_and_b64 s[14:15], s[14:15], exec
	v_cndmask_b32_e32 v45, v37, v39, vcc
	v_lshlrev_b32_e32 v45, 2, v45
	s_nop 0
	v_cmp_lt_i32_e32 vcc, v40, v38
	s_cselect_b32 s14, s18, 0x1c580000
	s_add_u32 s25, s22, s14
	s_addc_u32 s26, s23, 0
	s_waitcnt lgkmcnt(0)
	s_nop 1
	v_add_f32_dpp v46, v44, v44 quad_perm:[1,0,3,2] row_mask:0xf bank_mask:0xf
	v_cndmask_b32_e32 v44, v37, v40, vcc
	v_lshlrev_b32_e32 v44, 2, v44
	s_nop 0
	v_cmp_lt_i32_e32 vcc, v42, v38
	s_lshl_b64 s[14:15], s[10:11], 11
	s_add_u32 s14, s25, s14
	s_addc_u32 s15, s26, s15
	s_waitcnt lgkmcnt(0)
	s_nop 1
	v_add_f32_dpp v47, v46, v46 quad_perm:[2,3,0,1] row_mask:0xf bank_mask:0xf
	v_cndmask_b32_e32 v46, v37, v42, vcc
	v_lshlrev_b32_e32 v46, 2, v46
	s_nop 0
	v_cmp_lt_i32_e32 vcc, v43, v38
	v_cvt_pk_bf16_f32 v28, v28, v29
	v_cvt_pk_bf16_f32 v29, v30, v31
	global_store_dwordx2 v32, v[28:29], s[14:15]
	s_waitcnt lgkmcnt(0)
	s_nop 1
	v_add_f32_dpp v48, v47, v47 row_half_mirror row_mask:0xf bank_mask:0xf
	v_cndmask_b32_e32 v47, v37, v43, vcc
	v_lshlrev_b32_e32 v47, 2, v47
	s_nop 0
	v_cvt_pk_bf16_f32 v28, v24, v25
	v_xor_b32_e32 v24, 16, v37
	v_cmp_lt_i32_e32 vcc, v24, v38
	v_cvt_pk_bf16_f32 v29, v26, v27
	s_waitcnt lgkmcnt(0)
	s_nop 1
	v_add_f32_dpp v25, v48, v48 row_mirror row_mask:0xf bank_mask:0xf
	global_store_dwordx2 v32, v[28:29], s[14:15] offset:512
	v_cndmask_b32_e32 v24, v37, v24, vcc
	v_lshlrev_b32_e32 v24, 2, v24
	ds_bpermute_b32 v30, v24, v25
	v_cvt_pk_bf16_f32 v26, v20, v21
	v_xor_b32_e32 v20, 32, v37
	v_cmp_lt_i32_e32 vcc, v20, v38
	v_cvt_pk_bf16_f32 v27, v22, v23
	s_waitcnt lgkmcnt(0)
	v_add_f32_e32 v21, v25, v30
	global_store_dwordx2 v32, v[26:27], s[14:15] offset:1024
	v_cndmask_b32_e32 v20, v37, v20, vcc
	v_lshlrev_b32_e32 v20, 2, v20
	ds_bpermute_b32 v22, v20, v21
	v_cvt_pk_bf16_f32 v16, v16, v17
	v_cvt_pk_bf16_f32 v17, v18, v19
	global_store_dwordx2 v32, v[16:17], s[14:15] offset:1536
	s_mov_b64 s[14:15], -1
	s_waitcnt lgkmcnt(0)
	v_add_f32_e32 v16, v21, v22
	s_and_b64 vcc, exec, s[12:13]
	s_cbranch_vccz .LBB7_228
	s_and_saveexec_b64 s[12:13], s[6:7]
	s_cbranch_execz .LBB7_226
	v_fmamk_f32 v17, v16, 0x3a800000, v41
	v_mul_f32_e32 v18, 0x4b800000, v17
	v_cmp_gt_f32_e32 vcc, s19, v17
	s_lshl_b64 s[14:15], s[10:11], 2
	s_add_u32 s14, s16, s14
	v_cndmask_b32_e32 v17, v17, v18, vcc
	v_rsq_f32_e32 v17, v17
	s_addc_u32 s15, s17, s15
	v_mul_f32_e32 v18, 0x45800000, v17
	v_cndmask_b32_e32 v17, v17, v18, vcc
	global_store_dword v33, v17, s[14:15]

.LBB7_232:
	v_mul_f32_e32 v16, v13, v13
	v_mul_f32_e32 v17, v15, v15
	v_fmac_f32_e32 v16, v12, v12
	v_fmac_f32_e32 v17, v14, v14
	v_add_f32_e32 v16, v16, v17
	v_mul_f32_e32 v17, v9, v9
	v_mul_f32_e32 v18, v11, v11
	v_fmac_f32_e32 v17, v8, v8
	v_fmac_f32_e32 v18, v10, v10
	v_add_f32_e32 v17, v17, v18
	v_add_f32_e32 v16, v17, v16
	v_mul_f32_e32 v17, v5, v5
	v_mul_f32_e32 v18, v7, v7
	v_fmac_f32_e32 v17, v4, v4
	v_fmac_f32_e32 v18, v6, v6
	v_add_f32_e32 v17, v17, v18
	v_add_f32_e32 v16, v17, v16
	v_mul_f32_e32 v17, v1, v1
	v_mul_f32_e32 v18, v3, v3
	v_fmac_f32_e32 v17, v0, v0
	v_fmac_f32_e32 v18, v2, v2
	v_add_f32_e32 v17, v17, v18
	v_add_f32_e32 v16, v17, v16
	s_nop 0
	s_add_i32 s10, s24, 0xffff8000
	s_cmp_lt_i32 s24, 0x8000
	s_cselect_b64 s[8:9], -1, 0
	s_and_b64 vcc, s[8:9], exec
	s_waitcnt lgkmcnt(0)
	s_nop 1
	v_add_f32_dpp v16, v16, v16 quad_perm:[1,0,3,2] row_mask:0xf bank_mask:0xf
	s_nop 0
	s_cselect_b32 s9, s18, 0x1c580000
	s_cselect_b32 s8, s24, s10
	s_add_u32 s12, s22, s9
	s_addc_u32 s13, s23, 0
	s_waitcnt lgkmcnt(0)
	s_nop 1
	v_add_f32_dpp v16, v16, v16 quad_perm:[2,3,0,1] row_mask:0xf bank_mask:0xf
	s_nop 0
	s_ashr_i32 s9, s8, 31
	s_lshl_b64 s[10:11], s[8:9], 11
	s_add_u32 s10, s12, s10
	s_addc_u32 s11, s13, s11
	s_waitcnt lgkmcnt(0)
	s_nop 1
	v_add_f32_dpp v18, v16, v16 row_half_mirror row_mask:0xf bank_mask:0xf
	s_nop 0
	v_cvt_pk_bf16_f32 v16, v12, v13
	v_cvt_pk_bf16_f32 v17, v14, v15
	global_store_dwordx2 v32, v[16:17], s[10:11]
	v_cvt_pk_bf16_f32 v16, v8, v9
	s_waitcnt lgkmcnt(0)
	s_nop 1
	v_add_f32_dpp v18, v18, v18 row_mirror row_mask:0xf bank_mask:0xf
	v_mov_b32_e32 v19, v18
	s_nop 1
	v_permlane16_swap_b32_e32 v18, v19
	v_cvt_pk_bf16_f32 v17, v10, v11
	global_store_dwordx2 v32, v[16:17], s[10:11] offset:512
	v_cvt_pk_bf16_f32 v16, v4, v5
	v_cvt_pk_bf16_f32 v17, v6, v7
	s_waitcnt lgkmcnt(0)
	v_add_f32_e32 v18, v18, v19
	v_mov_b32_e32 v19, v18
	s_nop 1
	v_permlane32_swap_b32_e32 v18, v19
	global_store_dwordx2 v32, v[16:17], s[10:11] offset:1024
	v_cvt_pk_bf16_f32 v16, v0, v1
	v_cvt_pk_bf16_f32 v17, v2, v3
	global_store_dwordx2 v32, v[16:17], s[10:11] offset:1536
	s_waitcnt lgkmcnt(0)
	v_add_f32_e32 v16, v18, v19
	s_mov_b64 s[10:11], -1
	s_cbranch_vccnz .LBB7_236
	s_and_saveexec_b64 s[10:11], s[6:7]
	s_cbranch_execz .LBB7_235
	v_fmamk_f32 v17, v16, 0x3a800000, v41
	v_mul_f32_e32 v18, 0x4b800000, v17
	v_cmp_gt_f32_e32 vcc, s19, v17
	s_lshl_b64 s[12:13], s[8:9], 2
	s_add_u32 s12, s16, s12
	v_cndmask_b32_e32 v17, v17, v18, vcc
	v_rsq_f32_e32 v17, v17
	s_addc_u32 s13, s17, s13
	v_mul_f32_e32 v18, 0x45800000, v17
	v_cndmask_b32_e32 v17, v17, v18, vcc
	global_store_dword v33, v17, s[12:13]

.LBB7_805:
	s_or_b64 exec, exec, s[0:1]
	v_add_u32_e32 v0, s31, v12
	s_waitcnt lgkmcnt(0)
	s_barrier
	ds_read2_b64 v[2:5], v0 offset1:1
	s_add_i32 s0, s13, s86
	s_ashr_i32 s1, s0, 31
	s_lshl_b64 s[0:1], s[0:1], 11
	s_add_i32 s12, s12, s60
	s_waitcnt lgkmcnt(0)
	v_add_f32_e32 v6, 0, v2
	v_add_f32_e32 v8, v6, v3
	ds_read_b64 v[6:7], v0 offset:16
	v_add_f32_e32 v0, v8, v4
	v_add_f32_e32 v0, v0, v5
	s_waitcnt lgkmcnt(0)
	v_add_f32_e32 v0, v0, v6
	v_add_f32_e32 v0, v0, v7
	s_nop 0
	s_waitcnt lgkmcnt(0)
	s_nop 1
	v_add_f32_dpp v0, v0, v0 quad_perm:[1,0,3,2] row_mask:0xf bank_mask:0xf
	s_nop 0
	s_waitcnt lgkmcnt(0)
	s_nop 1
	v_add_f32_dpp v0, v0, v0 quad_perm:[2,3,0,1] row_mask:0xf bank_mask:0xf
	s_nop 0
	s_waitcnt lgkmcnt(0)
	s_nop 1
	v_add_f32_dpp v0, v0, v0 row_half_mirror row_mask:0xf bank_mask:0xf
	s_nop 0
	s_waitcnt lgkmcnt(0)
	s_nop 1
	v_add_f32_dpp v0, v0, v0 row_mirror row_mask:0xf bank_mask:0xf
	v_mov_b32_e32 v8, v0
	s_nop 1
	v_permlane16_swap_b32_e32 v0, v8
	s_waitcnt lgkmcnt(0)
	v_add_f32_e32 v0, v0, v8
	v_mov_b32_e32 v8, v0
	s_nop 1
	v_permlane32_swap_b32_e32 v0, v8
	s_waitcnt lgkmcnt(0)
	v_add_f32_e32 v8, v0, v8
	v_mul_f32_e32 v0, 0x3b2aaaab, v8
	v_fmac_f32_e32 v3, 0xbb2aaaab, v8
	v_fmamk_f32 v2, v8, 0xbb2aaaab, v2
	v_mul_f32_e32 v78, v3, v3
	v_pk_add_f32 v[8:9], v[4:5], v[0:1] op_sel_hi:[1,0] neg_lo:[0,1] neg_hi:[0,1]
	v_fmac_f32_e32 v78, v2, v2
	v_pk_mul_f32 v[4:5], v[8:9], v[8:9]
	v_pk_add_f32 v[82:83], v[6:7], v[0:1] op_sel_hi:[1,0] neg_lo:[0,1] neg_hi:[0,1]
	v_add_f32_e32 v4, v4, v78
	v_add_f32_e32 v78, v5, v4
	v_pk_mul_f32 v[4:5], v[82:83], v[82:83]
	s_nop 0
	v_add_f32_e32 v0, v4, v78
	v_add_f32_e32 v0, v5, v0
	s_nop 0
	s_waitcnt lgkmcnt(0)
	s_nop 1
	v_add_f32_dpp v0, v0, v0 quad_perm:[1,0,3,2] row_mask:0xf bank_mask:0xf
	s_nop 0
	s_waitcnt lgkmcnt(0)
	s_nop 1
	v_add_f32_dpp v0, v0, v0 quad_perm:[2,3,0,1] row_mask:0xf bank_mask:0xf
	s_nop 0
	s_waitcnt lgkmcnt(0)
	s_nop 1
	v_add_f32_dpp v0, v0, v0 row_half_mirror row_mask:0xf bank_mask:0xf
	s_nop 0
	s_waitcnt lgkmcnt(0)
	s_nop 1
	v_add_f32_dpp v0, v0, v0 row_mirror row_mask:0xf bank_mask:0xf
	v_mov_b32_e32 v4, v0
	s_nop 1
	v_permlane16_swap_b32_e32 v0, v4
	s_waitcnt lgkmcnt(0)
	v_add_f32_e32 v0, v0, v4
	v_mov_b32_e32 v4, v0
	s_nop 1
	v_permlane32_swap_b32_e32 v0, v4
	s_waitcnt lgkmcnt(0)
	v_add_f32_e32 v0, v0, v4
	v_fmamk_f32 v0, v0, 0x3b2aaaab, v162
	v_cmp_gt_f32_e64 s[42:43], s11, v0
	v_mul_f32_e32 v4, 0x4b800000, v0
	s_nop 0
	v_cndmask_b32_e64 v0, v0, v4, s[42:43]
	v_rsq_f32_e32 v0, v0
	s_nop 0
	v_mul_f32_e32 v4, 0x45800000, v0
	v_cndmask_b32_e64 v0, v0, v4, s[42:43]
	global_load_dwordx2 v[84:85], v[72:73], off offset:16
	global_load_dwordx4 v[4:7], v[72:73], off
	global_load_dwordx2 v[86:87], v[74:75], off offset:16
	global_load_dwordx4 v[78:81], v[74:75], off
	v_mul_f32_e32 v2, v2, v0
	s_waitcnt vmcnt(0)
	v_fma_f32 v2, v4, v2, v78
	v_mul_f32_e32 v4, 0xbfb8aa3b, v2
	v_exp_f32_e32 v4, v4
	s_nop 0
	v_add_f32_e32 v4, 1.0, v4
	v_rcp_f32_e32 v4, v4
	s_nop 0
	v_mul_f32_e32 v4, v2, v4
	v_mul_f32_e32 v2, v3, v0
	v_fma_f32 v2, v5, v2, v79
	v_mul_f32_e32 v3, 0xbfb8aa3b, v2
	v_exp_f32_e32 v3, v3
	s_nop 0
	v_add_f32_e32 v3, 1.0, v3
	v_rcp_f32_e32 v3, v3
	s_nop 0
	v_mul_f32_e32 v5, v2, v3
	v_mul_f32_e32 v2, v8, v0
	v_fma_f32 v2, v6, v2, v80
	v_mul_f32_e32 v3, 0xbfb8aa3b, v2
	v_exp_f32_e32 v3, v3
	v_cvt_pk_bf16_f32 v4, v4, v5
	s_nop 0
	v_add_f32_e32 v3, 1.0, v3
	v_rcp_f32_e32 v3, v3
	s_nop 0
	v_mul_f32_e32 v6, v2, v3
	v_mul_f32_e32 v2, v9, v0
	v_fmac_f32_e32 v81, v7, v2
	v_mul_f32_e32 v2, 0xbfb8aa3b, v81
	v_exp_f32_e32 v2, v2
	s_nop 0
	v_add_f32_e32 v2, 1.0, v2
	v_rcp_f32_e32 v2, v2
	s_nop 0
	v_mul_f32_e32 v7, v81, v2
	v_mul_f32_e32 v2, v82, v0
	v_mul_f32_e32 v0, v83, v0
	v_fma_f32 v2, v84, v2, v86
	v_fmac_f32_e32 v87, v85, v0
	v_mul_f32_e32 v3, 0xbfb8aa3b, v2
	v_mul_f32_e32 v0, 0xbfb8aa3b, v87
	v_exp_f32_e32 v3, v3
	v_exp_f32_e32 v0, v0
	v_add_f32_e32 v3, 1.0, v3
	v_add_f32_e32 v0, 1.0, v0
	v_rcp_f32_e32 v3, v3
	v_rcp_f32_e32 v0, v0
	v_mul_f32_e32 v8, v2, v3
	v_mul_f32_e32 v0, v87, v0
	v_lshl_add_u64 v[2:3], v[76:77], 0, s[0:1]
	global_store_dword v[2:3], v4, off offset:1280
	v_cvt_pk_bf16_f32 v4, v6, v7
	global_store_dword v[2:3], v4, off offset:1284
	v_cvt_pk_bf16_f32 v0, v8, v0
	s_mul_i32 s0, s91, 0x600
	global_store_dword v[2:3], v0, off offset:1288
	v_add_u32_e32 v0, s0, v12
	ds_read2_b64 v[2:5], v0 offset1:1
	s_add_i32 s0, s13, s91
	s_ashr_i32 s1, s0, 31
	s_lshl_b64 s[0:1], s[0:1], 11
	s_waitcnt lgkmcnt(0)
	v_add_f32_e32 v6, 0, v2
	v_add_f32_e32 v8, v6, v3
	ds_read_b64 v[6:7], v0 offset:16
	v_add_f32_e32 v8, v8, v4
	v_add_f32_e32 v8, v8, v5
	s_waitcnt lgkmcnt(0)
	v_add_f32_e32 v8, v8, v6
	v_add_f32_e32 v8, v8, v7
	s_nop 0
	s_waitcnt lgkmcnt(0)
	s_nop 1
	v_add_f32_dpp v8, v8, v8 quad_perm:[1,0,3,2] row_mask:0xf bank_mask:0xf
	s_nop 0
	s_waitcnt lgkmcnt(0)
	s_nop 1
	v_add_f32_dpp v8, v8, v8 quad_perm:[2,3,0,1] row_mask:0xf bank_mask:0xf
	s_nop 0
	s_waitcnt lgkmcnt(0)
	s_nop 1
	v_add_f32_dpp v8, v8, v8 row_half_mirror row_mask:0xf bank_mask:0xf
	s_nop 0
	s_waitcnt lgkmcnt(0)
	s_nop 1
	v_add_f32_dpp v8, v8, v8 row_mirror row_mask:0xf bank_mask:0xf
	v_mov_b32_e32 v9, v8
	s_nop 1
	v_permlane16_swap_b32_e32 v8, v9
	s_waitcnt lgkmcnt(0)
	v_add_f32_e32 v8, v8, v9
	v_mov_b32_e32 v9, v8
	s_nop 1
	v_permlane32_swap_b32_e32 v8, v9
	s_waitcnt lgkmcnt(0)
	v_add_f32_e32 v9, v8, v9
	v_fmac_f32_e32 v3, 0xbb2aaaab, v9
	v_mul_f32_e32 v8, 0x3b2aaaab, v9
	v_fmamk_f32 v2, v9, 0xbb2aaaab, v2
	v_mul_f32_e32 v9, v3, v3
	v_fmac_f32_e32 v9, v2, v2
	v_pk_add_f32 v[82:83], v[4:5], v[8:9] op_sel_hi:[1,0] neg_lo:[0,1] neg_hi:[0,1]
	s_nop 0
	v_pk_mul_f32 v[4:5], v[82:83], v[82:83]
	s_nop 0
	v_add_f32_e32 v4, v4, v9
	v_pk_add_f32 v[8:9], v[6:7], v[8:9] op_sel_hi:[1,0] neg_lo:[0,1] neg_hi:[0,1]
	v_add_f32_e32 v78, v5, v4
	v_pk_mul_f32 v[4:5], v[8:9], v[8:9]
	s_nop 0
	v_add_f32_e32 v4, v4, v78
	v_add_f32_e32 v4, v5, v4
	s_nop 0
	s_waitcnt lgkmcnt(0)
	s_nop 1
	v_add_f32_dpp v4, v4, v4 quad_perm:[1,0,3,2] row_mask:0xf bank_mask:0xf
	s_nop 0
	s_waitcnt lgkmcnt(0)
	s_nop 1
	v_add_f32_dpp v4, v4, v4 quad_perm:[2,3,0,1] row_mask:0xf bank_mask:0xf
	s_nop 0
	s_waitcnt lgkmcnt(0)
	s_nop 1
	v_add_f32_dpp v4, v4, v4 row_half_mirror row_mask:0xf bank_mask:0xf
	s_nop 0
	s_waitcnt lgkmcnt(0)
	s_nop 1
	v_add_f32_dpp v4, v4, v4 row_mirror row_mask:0xf bank_mask:0xf
	v_mov_b32_e32 v5, v4
	s_nop 1
	v_permlane16_swap_b32_e32 v4, v5
	s_waitcnt lgkmcnt(0)
	v_add_f32_e32 v4, v4, v5
	v_mov_b32_e32 v5, v4
	s_nop 1
	v_permlane32_swap_b32_e32 v4, v5
	s_waitcnt lgkmcnt(0)
	v_add_f32_e32 v4, v4, v5
	v_fmamk_f32 v4, v4, 0x3b2aaaab, v162
	v_cmp_gt_f32_e64 s[42:43], s11, v4
	v_mul_f32_e32 v5, 0x4b800000, v4
	s_nop 0
	v_cndmask_b32_e64 v4, v4, v5, s[42:43]
	v_rsq_f32_e32 v4, v4
	s_nop 0
	v_mul_f32_e32 v5, 0x45800000, v4
	v_cndmask_b32_e64 v88, v4, v5, s[42:43]
	global_load_dwordx2 v[84:85], v[72:73], off offset:16
	global_load_dwordx4 v[4:7], v[72:73], off
	global_load_dwordx2 v[86:87], v[74:75], off offset:16
	global_load_dwordx4 v[78:81], v[74:75], off
	v_mul_f32_e32 v2, v2, v88
	v_mul_f32_e32 v3, v3, v88
	s_waitcnt vmcnt(0)
	v_fma_f32 v2, v4, v2, v78
	v_mul_f32_e32 v4, 0xbfb8aa3b, v2
	v_exp_f32_e32 v4, v4
	v_fma_f32 v3, v5, v3, v79
	v_add_f32_e32 v4, 1.0, v4
	v_rcp_f32_e32 v4, v4
	s_nop 0
	v_mul_f32_e32 v2, v2, v4
	v_mul_f32_e32 v4, 0xbfb8aa3b, v3
	v_exp_f32_e32 v4, v4
	s_nop 0
	v_add_f32_e32 v4, 1.0, v4
	v_rcp_f32_e32 v4, v4
	s_nop 0
	v_mul_f32_e32 v3, v3, v4
	v_mul_f32_e32 v4, v82, v88
	v_fma_f32 v4, v6, v4, v80
	v_mul_f32_e32 v5, 0xbfb8aa3b, v4
	v_exp_f32_e32 v5, v5
	v_mul_f32_e32 v6, v8, v88
	v_fma_f32 v6, v84, v6, v86
	v_cvt_pk_bf16_f32 v2, v2, v3
	v_add_f32_e32 v5, 1.0, v5
	v_rcp_f32_e32 v5, v5
	s_nop 0
	v_mul_f32_e32 v4, v4, v5
	v_mul_f32_e32 v5, v83, v88
	v_fmac_f32_e32 v81, v7, v5
	v_mul_f32_e32 v7, 0xbfb8aa3b, v6
	v_exp_f32_e32 v7, v7
	v_mul_f32_e32 v5, 0xbfb8aa3b, v81
	v_exp_f32_e32 v5, v5
	v_add_f32_e32 v7, 1.0, v7
	v_rcp_f32_e32 v7, v7
	v_add_f32_e32 v5, 1.0, v5
	v_rcp_f32_e32 v5, v5
	v_mul_f32_e32 v6, v6, v7
	v_mul_f32_e32 v7, v9, v88
	v_fmac_f32_e32 v87, v85, v7
	v_mul_f32_e32 v7, 0xbfb8aa3b, v87
	v_exp_f32_e32 v7, v7
	v_lshl_add_u64 v[8:9], v[76:77], 0, s[0:1]
	v_mul_f32_e32 v5, v81, v5
	global_store_dword v[8:9], v2, off offset:1280
	v_add_f32_e32 v7, 1.0, v7
	v_rcp_f32_e32 v7, v7
	v_cvt_pk_bf16_f32 v2, v4, v5
	global_store_dword v[8:9], v2, off offset:1284
	s_add_i32 s0, s13, s93
	v_mul_f32_e32 v7, v87, v7
	v_cvt_pk_bf16_f32 v2, v6, v7
	global_store_dword v[8:9], v2, off offset:1288
	ds_read2_b64 v[2:5], v0 offset0:192 offset1:193
	s_ashr_i32 s1, s0, 31
	s_lshl_b64 s[0:1], s[0:1], 11
	s_waitcnt lgkmcnt(0)
	v_add_f32_e32 v6, 0, v2
	v_add_f32_e32 v8, v6, v3
	ds_read_b64 v[6:7], v0 offset:1552
	v_add_f32_e32 v8, v8, v4
	v_add_f32_e32 v8, v8, v5
	s_waitcnt lgkmcnt(0)
	v_add_f32_e32 v8, v8, v6
	v_add_f32_e32 v8, v8, v7
	s_nop 0
	s_waitcnt lgkmcnt(0)
	s_nop 1
	v_add_f32_dpp v8, v8, v8 quad_perm:[1,0,3,2] row_mask:0xf bank_mask:0xf
	s_nop 0
	s_waitcnt lgkmcnt(0)
	s_nop 1
	v_add_f32_dpp v8, v8, v8 quad_perm:[2,3,0,1] row_mask:0xf bank_mask:0xf
	s_nop 0
	s_waitcnt lgkmcnt(0)
	s_nop 1
	v_add_f32_dpp v8, v8, v8 row_half_mirror row_mask:0xf bank_mask:0xf
	s_nop 0
	s_waitcnt lgkmcnt(0)
	s_nop 1
	v_add_f32_dpp v8, v8, v8 row_mirror row_mask:0xf bank_mask:0xf
	v_mov_b32_e32 v9, v8
	s_nop 1
	v_permlane16_swap_b32_e32 v8, v9
	s_waitcnt lgkmcnt(0)
	v_add_f32_e32 v8, v8, v9
	v_mov_b32_e32 v9, v8
	s_nop 1
	v_permlane32_swap_b32_e32 v8, v9
	s_waitcnt lgkmcnt(0)
	v_add_f32_e32 v9, v8, v9
	v_fmac_f32_e32 v3, 0xbb2aaaab, v9
	v_mul_f32_e32 v8, 0x3b2aaaab, v9
	v_fmamk_f32 v2, v9, 0xbb2aaaab, v2
	v_mul_f32_e32 v9, v3, v3
	v_fmac_f32_e32 v9, v2, v2
	v_pk_add_f32 v[82:83], v[4:5], v[8:9] op_sel_hi:[1,0] neg_lo:[0,1] neg_hi:[0,1]
	s_nop 0
	v_pk_mul_f32 v[4:5], v[82:83], v[82:83]
	s_nop 0
	v_add_f32_e32 v4, v4, v9
	v_pk_add_f32 v[8:9], v[6:7], v[8:9] op_sel_hi:[1,0] neg_lo:[0,1] neg_hi:[0,1]
	v_add_f32_e32 v78, v5, v4
	v_pk_mul_f32 v[4:5], v[8:9], v[8:9]
	s_nop 0
	v_add_f32_e32 v4, v4, v78
	v_add_f32_e32 v4, v5, v4
	s_nop 0
	s_waitcnt lgkmcnt(0)
	s_nop 1
	v_add_f32_dpp v4, v4, v4 quad_perm:[1,0,3,2] row_mask:0xf bank_mask:0xf
	s_nop 0
	s_waitcnt lgkmcnt(0)
	s_nop 1
	v_add_f32_dpp v4, v4, v4 quad_perm:[2,3,0,1] row_mask:0xf bank_mask:0xf
	s_nop 0
	s_waitcnt lgkmcnt(0)
	s_nop 1
	v_add_f32_dpp v4, v4, v4 row_half_mirror row_mask:0xf bank_mask:0xf
	s_nop 0
	s_waitcnt lgkmcnt(0)
	s_nop 1
	v_add_f32_dpp v4, v4, v4 row_mirror row_mask:0xf bank_mask:0xf
	v_mov_b32_e32 v5, v4
	s_nop 1
	v_permlane16_swap_b32_e32 v4, v5
	s_waitcnt lgkmcnt(0)
	v_add_f32_e32 v4, v4, v5
	v_mov_b32_e32 v5, v4
	s_nop 1
	v_permlane32_swap_b32_e32 v4, v5
	s_waitcnt lgkmcnt(0)
	v_add_f32_e32 v4, v4, v5
	v_fmamk_f32 v4, v4, 0x3b2aaaab, v162
	v_cmp_gt_f32_e64 s[42:43], s11, v4
	v_mul_f32_e32 v5, 0x4b800000, v4
	s_nop 0
	v_cndmask_b32_e64 v4, v4, v5, s[42:43]
	v_rsq_f32_e32 v4, v4
	s_nop 0
	v_mul_f32_e32 v5, 0x45800000, v4
	v_cndmask_b32_e64 v88, v4, v5, s[42:43]
	global_load_dwordx2 v[84:85], v[72:73], off offset:16
	global_load_dwordx4 v[4:7], v[72:73], off
	global_load_dwordx2 v[86:87], v[74:75], off offset:16
	global_load_dwordx4 v[78:81], v[74:75], off
	v_mul_f32_e32 v2, v2, v88
	s_waitcnt vmcnt(0)
	v_fma_f32 v2, v4, v2, v78
	v_mul_f32_e32 v4, 0xbfb8aa3b, v2
	v_exp_f32_e32 v4, v4
	s_nop 0
	v_add_f32_e32 v4, 1.0, v4
	v_rcp_f32_e32 v4, v4
	s_nop 0
	v_mul_f32_e32 v4, v2, v4
	v_mul_f32_e32 v2, v3, v88
	v_fma_f32 v2, v5, v2, v79
	v_mul_f32_e32 v3, 0xbfb8aa3b, v2
	v_exp_f32_e32 v3, v3
	s_nop 0
	v_add_f32_e32 v3, 1.0, v3
	v_rcp_f32_e32 v3, v3
	s_nop 0
	v_mul_f32_e32 v5, v2, v3
	v_mul_f32_e32 v2, v82, v88
	v_fma_f32 v2, v6, v2, v80
	v_mul_f32_e32 v3, 0xbfb8aa3b, v2
	v_exp_f32_e32 v3, v3
	v_cvt_pk_bf16_f32 v4, v4, v5
	s_nop 0
	v_add_f32_e32 v3, 1.0, v3
	v_rcp_f32_e32 v3, v3
	s_nop 0
	v_mul_f32_e32 v6, v2, v3
	v_mul_f32_e32 v2, v83, v88
	v_fmac_f32_e32 v81, v7, v2
	v_mul_f32_e32 v2, 0xbfb8aa3b, v81
	v_exp_f32_e32 v2, v2
	s_nop 0
	v_add_f32_e32 v2, 1.0, v2
	v_rcp_f32_e32 v2, v2
	s_nop 0
	v_mul_f32_e32 v7, v81, v2
	v_mul_f32_e32 v2, v8, v88
	v_fma_f32 v2, v84, v2, v86
	v_mul_f32_e32 v3, 0xbfb8aa3b, v2
	v_exp_f32_e32 v3, v3
	s_nop 0
	v_add_f32_e32 v3, 1.0, v3
	v_rcp_f32_e32 v3, v3
	s_nop 0
	v_mul_f32_e32 v8, v2, v3
	v_mul_f32_e32 v2, v9, v88
	v_fmac_f32_e32 v87, v85, v2
	v_mul_f32_e32 v2, 0xbfb8aa3b, v87
	v_exp_f32_e32 v2, v2
	s_nop 0
	v_add_f32_e32 v2, 1.0, v2
	v_rcp_f32_e32 v2, v2
	s_nop 0
	v_mul_f32_e32 v9, v87, v2
	v_lshl_add_u64 v[2:3], v[76:77], 0, s[0:1]
	global_store_dword v[2:3], v4, off offset:1280
	v_cvt_pk_bf16_f32 v4, v6, v7
	global_store_dword v[2:3], v4, off offset:1284
	v_cvt_pk_bf16_f32 v4, v8, v9
	global_store_dword v[2:3], v4, off offset:1288
	v_add_u32_e32 v2, 0xc00, v0
	ds_read2_b64 v[2:5], v2 offset1:1
	s_add_i32 s0, s13, s28
	s_ashr_i32 s1, s0, 31
	s_lshl_b64 s[0:1], s[0:1], 11
	s_cmpk_lt_i32 s12, 0x400
	s_waitcnt lgkmcnt(0)
	v_add_f32_e32 v6, 0, v2
	v_add_f32_e32 v8, v6, v3
	ds_read_b64 v[6:7], v0 offset:3088
	v_add_f32_e32 v0, v8, v4
	v_add_f32_e32 v0, v0, v5
	s_waitcnt lgkmcnt(0)
	v_add_f32_e32 v0, v0, v6
	v_add_f32_e32 v0, v0, v7
	s_nop 0
	s_waitcnt lgkmcnt(0)
	s_nop 1
	v_add_f32_dpp v0, v0, v0 quad_perm:[1,0,3,2] row_mask:0xf bank_mask:0xf
	s_nop 0
	s_waitcnt lgkmcnt(0)
	s_nop 1
	v_add_f32_dpp v0, v0, v0 quad_perm:[2,3,0,1] row_mask:0xf bank_mask:0xf
	s_nop 0
	s_waitcnt lgkmcnt(0)
	s_nop 1
	v_add_f32_dpp v0, v0, v0 row_half_mirror row_mask:0xf bank_mask:0xf
	s_nop 0
	s_waitcnt lgkmcnt(0)
	s_nop 1
	v_add_f32_dpp v0, v0, v0 row_mirror row_mask:0xf bank_mask:0xf
	v_mov_b32_e32 v8, v0
	s_nop 1
	v_permlane16_swap_b32_e32 v0, v8
	s_waitcnt lgkmcnt(0)
	v_add_f32_e32 v0, v0, v8
	v_mov_b32_e32 v8, v0
	s_nop 1
	v_permlane32_swap_b32_e32 v0, v8
	s_waitcnt lgkmcnt(0)
	v_add_f32_e32 v8, v0, v8
	v_mul_f32_e32 v0, 0x3b2aaaab, v8
	v_fmac_f32_e32 v3, 0xbb2aaaab, v8
	v_fmamk_f32 v2, v8, 0xbb2aaaab, v2
	v_mul_f32_e32 v78, v3, v3
	v_pk_add_f32 v[8:9], v[4:5], v[0:1] op_sel_hi:[1,0] neg_lo:[0,1] neg_hi:[0,1]
	v_fmac_f32_e32 v78, v2, v2
	v_pk_mul_f32 v[4:5], v[8:9], v[8:9]
	v_pk_add_f32 v[82:83], v[6:7], v[0:1] op_sel_hi:[1,0] neg_lo:[0,1] neg_hi:[0,1]
	v_add_f32_e32 v4, v4, v78
	v_add_f32_e32 v78, v5, v4
	v_pk_mul_f32 v[4:5], v[82:83], v[82:83]
	s_nop 0
	v_add_f32_e32 v0, v4, v78
	v_add_f32_e32 v0, v5, v0
	s_nop 0
	s_waitcnt lgkmcnt(0)
	s_nop 1
	v_add_f32_dpp v0, v0, v0 quad_perm:[1,0,3,2] row_mask:0xf bank_mask:0xf
	s_nop 0
	s_waitcnt lgkmcnt(0)
	s_nop 1
	v_add_f32_dpp v0, v0, v0 quad_perm:[2,3,0,1] row_mask:0xf bank_mask:0xf
	s_nop 0
	s_waitcnt lgkmcnt(0)
	s_nop 1
	v_add_f32_dpp v0, v0, v0 row_half_mirror row_mask:0xf bank_mask:0xf
	s_nop 0
	s_waitcnt lgkmcnt(0)
	s_nop 1
	v_add_f32_dpp v0, v0, v0 row_mirror row_mask:0xf bank_mask:0xf
	v_mov_b32_e32 v4, v0
	s_nop 1
	v_permlane16_swap_b32_e32 v0, v4
	s_waitcnt lgkmcnt(0)
	v_add_f32_e32 v0, v0, v4
	v_mov_b32_e32 v4, v0
	s_nop 1
	v_permlane32_swap_b32_e32 v0, v4
	s_waitcnt lgkmcnt(0)
	v_add_f32_e32 v0, v0, v4
	v_fmamk_f32 v0, v0, 0x3b2aaaab, v162
	v_cmp_gt_f32_e64 s[42:43], s11, v0
	v_mul_f32_e32 v4, 0x4b800000, v0
	s_nop 0
	v_cndmask_b32_e64 v0, v0, v4, s[42:43]
	v_rsq_f32_e32 v0, v0
	s_nop 0
	v_mul_f32_e32 v4, 0x45800000, v0
	v_cndmask_b32_e64 v0, v0, v4, s[42:43]
	global_load_dwordx2 v[84:85], v[72:73], off offset:16
	global_load_dwordx4 v[4:7], v[72:73], off
	global_load_dwordx2 v[86:87], v[74:75], off offset:16
	global_load_dwordx4 v[78:81], v[74:75], off
	v_mul_f32_e32 v2, v2, v0
	s_waitcnt vmcnt(0)
	v_fma_f32 v2, v4, v2, v78
	v_mul_f32_e32 v4, 0xbfb8aa3b, v2
	v_exp_f32_e32 v4, v4
	s_nop 0
	v_add_f32_e32 v4, 1.0, v4
	v_rcp_f32_e32 v4, v4
	s_nop 0
	v_mul_f32_e32 v4, v2, v4
	v_mul_f32_e32 v2, v3, v0
	v_fma_f32 v2, v5, v2, v79
	v_mul_f32_e32 v3, 0xbfb8aa3b, v2
	v_exp_f32_e32 v3, v3
	s_nop 0
	v_add_f32_e32 v3, 1.0, v3
	v_rcp_f32_e32 v3, v3
	s_nop 0
	v_mul_f32_e32 v5, v2, v3
	v_mul_f32_e32 v2, v8, v0
	v_fma_f32 v2, v6, v2, v80
	v_mul_f32_e32 v3, 0xbfb8aa3b, v2
	v_exp_f32_e32 v3, v3
	v_cvt_pk_bf16_f32 v4, v4, v5
	s_nop 0
	v_add_f32_e32 v3, 1.0, v3
	v_rcp_f32_e32 v3, v3
	s_nop 0
	v_mul_f32_e32 v6, v2, v3
	v_mul_f32_e32 v2, v9, v0
	v_fmac_f32_e32 v81, v7, v2
	v_mul_f32_e32 v2, 0xbfb8aa3b, v81
	v_exp_f32_e32 v2, v2
	s_nop 0
	v_add_f32_e32 v2, 1.0, v2
	v_rcp_f32_e32 v2, v2
	s_nop 0
	v_mul_f32_e32 v7, v81, v2
	v_mul_f32_e32 v2, v82, v0
	v_mul_f32_e32 v0, v83, v0
	v_fma_f32 v2, v84, v2, v86
	v_fmac_f32_e32 v87, v85, v0
	v_mul_f32_e32 v3, 0xbfb8aa3b, v2
	v_mul_f32_e32 v0, 0xbfb8aa3b, v87
	v_exp_f32_e32 v3, v3
	v_exp_f32_e32 v0, v0
	v_add_f32_e32 v3, 1.0, v3
	v_add_f32_e32 v0, 1.0, v0
	v_rcp_f32_e32 v3, v3
	v_rcp_f32_e32 v0, v0
	v_mul_f32_e32 v8, v2, v3
	v_mul_f32_e32 v0, v87, v0
	v_lshl_add_u64 v[2:3], v[76:77], 0, s[0:1]
	global_store_dword v[2:3], v4, off offset:1280
	v_cvt_pk_bf16_f32 v4, v6, v7
	global_store_dword v[2:3], v4, off offset:1284
	v_cvt_pk_bf16_f32 v0, v8, v0
	global_store_dword v[2:3], v0, off offset:1288
	s_cbranch_scc0 .LBB7_813
